# count polling on top of early-inv barrier (waiters poll the arrival counter); expected slower, recorded for comparison
# baseline (speedup 1.0000x reference)
.Lea_0:
.LBB0_196:
	s_or_b64 exec, exec, s[8:9]
	v_cvt_f32_u32_e32 v4, v2
	s_waitcnt vmcnt(0)
	v_readfirstlane_b32 s4, v3
	v_sub_u32_e32 v3, 0, v2
	v_rcp_iflag_f32_e32 v4, v4
	v_add_u32_e32 v5, s4, v1
	v_mul_f32_e32 v4, 0x4f7ffffe, v4
	v_cvt_u32_f32_e32 v4, v4
	v_mul_lo_u32 v1, v3, v4
	v_mul_hi_u32 v1, v4, v1
	v_add_u32_e32 v1, v4, v1
	v_mul_hi_u32 v1, v5, v1
	v_mul_lo_u32 v3, v1, v2
	v_sub_u32_e32 v3, v5, v3
	v_add_u32_e32 v4, 1, v1
	v_cmp_ge_u32_e32 vcc, v3, v2
	s_nop 1
	v_cndmask_b32_e32 v1, v1, v4, vcc
	v_sub_u32_e32 v4, v3, v2
	v_cndmask_b32_e32 v3, v3, v4, vcc
	v_add_u32_e32 v4, 1, v1
	v_cmp_ge_u32_e32 vcc, v3, v2
	v_add_u32_e32 v3, 1, v5
	s_nop 0
	v_cndmask_b32_e32 v1, v1, v4, vcc
	v_mul_lo_u32 v4, v2, v1
	v_add_u32_e32 v2, v4, v2
	v_cmp_ne_u32_e32 vcc, v3, v2
	s_and_saveexec_b64 s[4:5], vcc
	s_xor_b64 s[8:9], exec, s[4:5]
	s_cbranch_execz .LBB0_210
	s_cmp_lg_u32 s101, 0
	s_cselect_b32 s98, 26, 28
	s_cselect_b32 s99, 27, 29
	s_nop 3
	v_readlane_b32 s4, v254, s98
	v_readlane_b32 s5, v254, s99
	s_waitcnt lgkmcnt(0)
	s_nop 3
	global_load_dword v0, v177, s[4:5] sc1
	s_waitcnt vmcnt(0)
	s_cmp_lg_u32 s101, 0
	s_cbranch_scc0 .Lpc_0
	v_cmp_ge_u32_e32 vcc, v0, v2
	s_nop 1
	v_addc_co_u32_e32 v0, vcc, 0, v1, vcc

.Lea_1:
.LBB0_346:
	s_or_b64 exec, exec, s[6:7]
	v_cvt_f32_u32_e32 v4, v2
	s_waitcnt vmcnt(0)
	v_readfirstlane_b32 s4, v3
	v_sub_u32_e32 v3, 0, v2
	v_rcp_iflag_f32_e32 v4, v4
	v_add_u32_e32 v5, s4, v1
	v_mul_f32_e32 v4, 0x4f7ffffe, v4
	v_cvt_u32_f32_e32 v4, v4
	v_mul_lo_u32 v1, v3, v4
	v_mul_hi_u32 v1, v4, v1
	v_add_u32_e32 v1, v4, v1
	v_mul_hi_u32 v1, v5, v1
	v_mul_lo_u32 v3, v1, v2
	v_sub_u32_e32 v3, v5, v3
	v_add_u32_e32 v4, 1, v1
	v_cmp_ge_u32_e32 vcc, v3, v2
	s_nop 1
	v_cndmask_b32_e32 v1, v1, v4, vcc
	v_sub_u32_e32 v4, v3, v2
	v_cndmask_b32_e32 v3, v3, v4, vcc
	v_add_u32_e32 v4, 1, v1
	v_cmp_ge_u32_e32 vcc, v3, v2
	v_add_u32_e32 v3, 1, v5
	s_nop 0
	v_cndmask_b32_e32 v1, v1, v4, vcc
	v_mul_lo_u32 v4, v2, v1
	v_add_u32_e32 v2, v4, v2
	v_cmp_ne_u32_e32 vcc, v3, v2
	s_and_saveexec_b64 s[4:5], vcc
	s_xor_b64 s[6:7], exec, s[4:5]
	s_cbranch_execz .LBB0_360
	s_cmp_lg_u32 s101, 0
	s_cselect_b32 s98, 26, 28
	s_cselect_b32 s99, 27, 29
	s_nop 3
	v_readlane_b32 s4, v254, s98
	v_readlane_b32 s5, v254, s99
	s_waitcnt lgkmcnt(0)
	s_nop 3
	global_load_dword v0, v177, s[4:5] sc1
	s_waitcnt vmcnt(0)
	s_cmp_lg_u32 s101, 0
	s_cbranch_scc0 .Lpc_2
	v_cmp_ge_u32_e32 vcc, v0, v2
	s_nop 1
	v_addc_co_u32_e32 v0, vcc, 0, v1, vcc

.Lea_4:
.LBB0_745:
	s_or_b64 exec, exec, s[6:7]
	v_cvt_f32_u32_e32 v4, v2
	s_waitcnt vmcnt(0)
	v_readfirstlane_b32 s4, v3
	v_sub_u32_e32 v3, 0, v2
	v_rcp_iflag_f32_e32 v4, v4
	v_add_u32_e32 v5, s4, v1
	v_mul_f32_e32 v4, 0x4f7ffffe, v4
	v_cvt_u32_f32_e32 v4, v4
	v_mul_lo_u32 v1, v3, v4
	v_mul_hi_u32 v1, v4, v1
	v_add_u32_e32 v1, v4, v1
	v_mul_hi_u32 v1, v5, v1
	v_mul_lo_u32 v3, v1, v2
	v_sub_u32_e32 v3, v5, v3
	v_add_u32_e32 v4, 1, v1
	v_cmp_ge_u32_e32 vcc, v3, v2
	s_nop 1
	v_cndmask_b32_e32 v1, v1, v4, vcc
	v_sub_u32_e32 v4, v3, v2
	v_cndmask_b32_e32 v3, v3, v4, vcc
	v_add_u32_e32 v4, 1, v1
	v_cmp_ge_u32_e32 vcc, v3, v2
	v_add_u32_e32 v3, 1, v5
	s_nop 0
	v_cndmask_b32_e32 v1, v1, v4, vcc
	v_mul_lo_u32 v4, v2, v1
	v_add_u32_e32 v2, v4, v2
	v_cmp_ne_u32_e32 vcc, v3, v2
	s_and_saveexec_b64 s[6:7], vcc
	s_xor_b64 s[6:7], exec, s[6:7]
	s_cbranch_execz .LBB0_759
	s_cmp_lg_u32 s101, 0
	s_cselect_b32 s98, 26, 28
	s_cselect_b32 s99, 27, 29
	s_nop 3
	v_readlane_b32 s8, v254, s98
	v_readlane_b32 s9, v254, s99
	s_waitcnt lgkmcnt(0)
	s_nop 3
	global_load_dword v0, v181, s[8:9] sc1
	s_waitcnt vmcnt(0)
	s_cmp_lg_u32 s101, 0
	s_cbranch_scc0 .Lpc_8
	v_cmp_ge_u32_e32 vcc, v0, v2
	s_nop 1
	v_addc_co_u32_e32 v0, vcc, 0, v1, vcc
